# sc1 write-through on P9 fused-epilogue stores (cheaper L2 write-back at the grid barrier)
# baseline (speedup 1.0000x reference)
; __device__ __forceinline__ unsigned cvt_pk_bf16(float lo, float hi) { unsigned r; asm("v_cvt_pk_bf16_f32 %0, %1, %2" : "=v"(r) : "v"(lo), "v"(hi)); return r; }
; __device__ __forceinline__ float sigmoid_f(float v) { return __builtin_amdgcn_rcpf(1.0f + __builtin_amdgcn_exp2f(-1.4426950409f * v)); }
; __device__ __forceinline__ u32x4 pack8(f32x4 a, f32x4 b) { u32x4 w; w.x = cvt_pk_bf16(a[0], a[1]); w.y = cvt_pk_bf16(a[2], a[3]); w.z = cvt_pk_bf16(b[0], b[1]); w.w = cvt_pk_bf16(b[2], b[3]); return w; }
; __device__ __forceinline__ f32x4 bf4(u32x2 w) { return (f32x4){bf_lo(w.x), bf_hi(w.x), bf_lo(w.y), bf_hi(w.y)}; }
;     __device__ __forceinline__ void operator()(const f32x4 (&acc)[2][2][4][2], const Unit& u, int wr, int wc, int fr, int fq) const {
;     ...
;             for (int m = 0; m < 4; ++m) { const int row = row0 + ai * HALF + m * 16; bf16_t* rowp = UP + (size_t)row * 5632 + u.pn * HALF + wc * 32 + 8 * fq;
; #pragma unroll
;                 for (int bj = 0; bj < 2; ++bj) { const u32x4 w = pack8(acc[ai][bj][m][0], acc[ai][bj][m][1]); __builtin_nontemporal_store(w, (u32x4*)(rowp + (size_t)bj * ((size_t)16384 * 5632)));
;                     if (m == 3 && fr >= 14) *(u32x4*)(HALO + ((size_t)(row >> 6) * 2 + (fr - 14)) * 11264 + c0 + bj * HALF) = w; } }
; __device__ __forceinline__ void phase10(const Args& a, int G, int wv, bool dummy = false) {
;     ...
;             for (int t = 0; t < 8; ++t) { const f32x4 gc = bf4(gr[t]), vc = bf4(vr[t]);
;                 const f32x4 gg = wg0 * gm2 + wg1 * gm1 + wg2 * gc + bg, vv = wv0 * vm2 + wv1 * vm1 + wv2 * vc + bv;
;                 f32x4 o;
; #pragma unroll
;                 for (int e = 0; e < 4; ++e) o[e] = gg[e] * pg8::sigmoid_f(gg[e]) * vv[e];
;                 u32x2 w; w.x = cvt_pk_bf16(o[0], o[1]); w.y = cvt_pk_bf16(o[2], o[3]);
;                 if (dummy) *(u32x2*)((bf16_t*)(a.ws + WS_D) + ((((size_t)(row0 + t0 + t)) * 5632 + ch) & (size_t)0x1ffffff)) = w; else *(u32x2*)(up + (size_t)(t0 + t) * 5632) = w;
.Lcw_nonext:
	v_lshlrev_b32_e32 v148, 2, v152
	v_add_u32_e32 v148, s95, v148
	v_add_u32_e32 v148, 0x20000, v148
	ds_read_b128 v[156:159], v148
	ds_read_b128 v[160:163], v148 offset:16
	ds_read_b128 v[164:167], v148 offset:512
	ds_read_b128 v[168:171], v148 offset:528
	ds_read_b128 v[172:175], v148 offset:1024
	ds_read_b128 v[176:179], v148 offset:1040
	ds_read_b128 v[180:183], v148 offset:1536
	ds_read_b128 v[184:187], v148 offset:1552
	ds_read_b128 v[188:191], v148 offset:2048
	ds_read_b128 v[192:195], v148 offset:2064
	ds_read_b128 v[196:199], v148 offset:2560
	ds_read_b128 v[200:203], v148 offset:2576
	ds_read_b128 v[204:207], v148 offset:3072
	ds_read_b128 v[208:211], v148 offset:3088
	ds_read_b128 v[212:215], v148 offset:3584
	ds_read_b128 v[216:219], v148 offset:3600
	s_xor_b32 s95, s95, 0x1000
	v_add_u32_e32 v149, s52, v150
	v_mul_u32_u24_e32 v149, 0x2c00, v149
	v_lshl_add_u32 v149, v152, 1, v149
	v_mul_u32_u24_e32 v221, 0x5800, v150
	v_lshl_add_u32 v221, v152, 1, v221
	v_add_u32_e32 v220, 0xfffb3000, v221
	v_cmp_gt_u32_e64 s[64:65], 2, v150
	v_mov_b32_e32 v236, 0xbfb8aa3b
	v_mov_b32_e32 v238, 1.0
	v_mov_b32_e32 v239, 1.0
	s_lshl_b32 s21, s99, 9
	s_lshl_b32 s63, s98, 2
	s_lshr_b32 s66, s52, 6
	s_add_i32 s63, s63, s66
	s_mul_i32 s63, s63, 0xb000
	s_add_i32 s63, s63, s21
	s_add_u32 s34, s14, s63
	s_addc_u32 s35, s15, 0
	s_add_u32 s36, s12, 0xb000000
	s_addc_u32 s37, s13, 0
	s_add_u32 s36, s36, s63
	s_addc_u32 s37, s37, 0
	v_cvt_pk_bf16_f32 v222, v80, v81
	v_cvt_pk_bf16_f32 v223, v82, v83
	v_cvt_pk_bf16_f32 v224, v72, v73
	v_cvt_pk_bf16_f32 v225, v74, v75
	s_mov_b64 exec, s[2:3]
	global_store_dwordx4 v220, v[222:225], s[34:35] sc1
	s_mov_b64 exec, -1
	v_cvt_pk_bf16_f32 v226, v68, v69
	v_cvt_pk_bf16_f32 v227, v70, v71
	v_cvt_pk_bf16_f32 v228, v64, v65
	v_cvt_pk_bf16_f32 v229, v66, v67
	s_mov_b64 exec, s[2:3]
	global_store_dwordx4 v220, v[226:229], s[34:35] offset:256 sc1
	s_mov_b64 exec, -1
	v_cvt_pk_bf16_f32 v230, v124, v125
	v_cvt_pk_bf16_f32 v231, v126, v127
	v_cvt_pk_bf16_f32 v232, v120, v121
	v_cvt_pk_bf16_f32 v233, v122, v123
	s_mov_b64 exec, s[64:65]
	global_store_dwordx4 v221, v[230:233], s[36:37] sc1
	s_mov_b64 exec, -1
	v_cvt_pk_bf16_f32 v240, v116, v117
	v_cvt_pk_bf16_f32 v241, v118, v119
	v_cvt_pk_bf16_f32 v242, v108, v109
	v_cvt_pk_bf16_f32 v243, v110, v111
	s_mov_b64 exec, s[64:65]
	global_store_dwordx4 v221, v[240:243], s[36:37] offset:256 sc1
	s_mov_b64 exec, -1
	s_add_u32 s34, s34, 0x16000
	s_addc_u32 s35, s35, 0
	s_add_u32 s36, s36, 0x16000
	s_addc_u32 s37, s37, 0
	v_cvt_pk_bf16_f32 v222, v16, v17
	v_cvt_pk_bf16_f32 v223, v18, v19
	v_cvt_pk_bf16_f32 v224, v8, v9
	v_cvt_pk_bf16_f32 v225, v10, v11
	s_mov_b64 exec, s[2:3]
	global_store_dwordx4 v220, v[222:225], s[34:35] sc1
	s_mov_b64 exec, -1
	v_cvt_pk_bf16_f32 v226, v4, v5
	v_cvt_pk_bf16_f32 v227, v6, v7
	v_cvt_pk_bf16_f32 v228, v0, v1
	v_cvt_pk_bf16_f32 v229, v2, v3
	s_mov_b64 exec, s[2:3]
	global_store_dwordx4 v220, v[226:229], s[34:35] offset:256 sc1
	s_mov_b64 exec, -1
	v_cvt_pk_bf16_f32 v230, v60, v61
	v_cvt_pk_bf16_f32 v231, v62, v63
	v_cvt_pk_bf16_f32 v232, v56, v57
	v_cvt_pk_bf16_f32 v233, v58, v59
	s_mov_b64 exec, s[64:65]
	global_store_dwordx4 v221, v[230:233], s[36:37] sc1
	s_mov_b64 exec, -1
	v_cvt_pk_bf16_f32 v240, v52, v53
	v_cvt_pk_bf16_f32 v241, v54, v55
	v_cvt_pk_bf16_f32 v242, v44, v45
	v_cvt_pk_bf16_f32 v243, v46, v47
	s_mov_b64 exec, s[64:65]
	global_store_dwordx4 v221, v[240:243], s[36:37] offset:256 sc1
	s_mov_b64 exec, -1
	s_waitcnt lgkmcnt(0)
	s_nop 4
	s_mul_i32 s63, s98, 0x2c0000
	s_lshl_b32 s66, s99, 8
	s_add_u32 s63, s63, s66
	s_add_u32 s100, s12, s63
	s_addc_u32 s101, s13, 0
	v_pk_fma_f32 v[232:233], v[80:81], v[172:173], v[180:181]
	v_pk_fma_f32 v[234:235], v[68:69], v[204:205], v[212:213]
	s_nop 1
	v_fmac_f32_dpp v232, v80, v164 row_shr:1 row_mask:0xf bank_mask:0xf
	v_fmac_f32_dpp v233, v81, v165 row_shr:1 row_mask:0xf bank_mask:0xf
	v_fmac_f32_dpp v234, v68, v196 row_shr:1 row_mask:0xf bank_mask:0xf
	v_fmac_f32_dpp v235, v69, v197 row_shr:1 row_mask:0xf bank_mask:0xf
	v_fmac_f32_dpp v232, v80, v156 row_shr:2 row_mask:0xf bank_mask:0xf
	v_fmac_f32_dpp v233, v81, v157 row_shr:2 row_mask:0xf bank_mask:0xf
	v_fmac_f32_dpp v234, v68, v188 row_shr:2 row_mask:0xf bank_mask:0xf
	v_fmac_f32_dpp v235, v69, v189 row_shr:2 row_mask:0xf bank_mask:0xf
	v_fmac_f32_dpp v232, v96, v164 row_shl:15 row_mask:0xf bank_mask:0xf
	v_fmac_f32_dpp v233, v97, v165 row_shl:15 row_mask:0xf bank_mask:0xf
	v_fmac_f32_dpp v234, v84, v196 row_shl:15 row_mask:0xf bank_mask:0xf
	v_fmac_f32_dpp v235, v85, v197 row_shl:15 row_mask:0xf bank_mask:0xf
	v_fmac_f32_dpp v232, v96, v156 row_shl:14 row_mask:0xf bank_mask:0xf
	v_fmac_f32_dpp v233, v97, v157 row_shl:14 row_mask:0xf bank_mask:0xf
	v_fmac_f32_dpp v234, v84, v188 row_shl:14 row_mask:0xf bank_mask:0xf
	v_fmac_f32_dpp v235, v85, v189 row_shl:14 row_mask:0xf bank_mask:0xf
	v_mul_f32_e32 v246, v236, v232
	v_mul_f32_e32 v247, v236, v233
	v_exp_f32_e32 v246, v246
	v_exp_f32_e32 v247, v247
	s_nop 0
	v_pk_add_f32 v[246:247], v[246:247], v[238:239]
	v_rcp_f32_e32 v246, v246
	v_rcp_f32_e32 v247, v247
	v_pk_mul_f32 v[232:233], v[232:233], v[234:235]
	v_pk_mul_f32 v[232:233], v[232:233], v[246:247]
	v_cvt_pk_bf16_f32 v80, v232, v233
	v_pk_fma_f32 v[232:233], v[96:97], v[172:173], v[180:181]
	v_pk_fma_f32 v[234:235], v[84:85], v[204:205], v[212:213]
	s_nop 1
	v_fmac_f32_dpp v232, v96, v164 row_shr:1 row_mask:0xf bank_mask:0xf
	v_fmac_f32_dpp v233, v97, v165 row_shr:1 row_mask:0xf bank_mask:0xf
	v_fmac_f32_dpp v234, v84, v196 row_shr:1 row_mask:0xf bank_mask:0xf
	v_fmac_f32_dpp v235, v85, v197 row_shr:1 row_mask:0xf bank_mask:0xf
; __device__ __forceinline__ unsigned cvt_pk_bf16(float lo, float hi) { unsigned r; asm("v_cvt_pk_bf16_f32 %0, %1, %2" : "=v"(r) : "v"(lo), "v"(hi)); return r; }
; __device__ __forceinline__ float sigmoid_f(float v) { return __builtin_amdgcn_rcpf(1.0f + __builtin_amdgcn_exp2f(-1.4426950409f * v)); }
; __device__ __forceinline__ f32x4 bf4(u32x2 w) { return (f32x4){bf_lo(w.x), bf_hi(w.x), bf_lo(w.y), bf_hi(w.y)}; }
; __device__ __forceinline__ void phase10(const Args& a, int G, int wv, bool dummy = false) {
;     ...
;             for (int t = 0; t < 8; ++t) { const f32x4 gc = bf4(gr[t]), vc = bf4(vr[t]);
;                 const f32x4 gg = wg0 * gm2 + wg1 * gm1 + wg2 * gc + bg, vv = wv0 * vm2 + wv1 * vm1 + wv2 * vc + bv;
;                 f32x4 o;
; #pragma unroll
;                 for (int e = 0; e < 4; ++e) o[e] = gg[e] * pg8::sigmoid_f(gg[e]) * vv[e];
;                 u32x2 w; w.x = cvt_pk_bf16(o[0], o[1]); w.y = cvt_pk_bf16(o[2], o[3]);
;                 if (dummy) *(u32x2*)((bf16_t*)(a.ws + WS_D) + ((((size_t)(row0 + t0 + t)) * 5632 + ch) & (size_t)0x1ffffff)) = w; else *(u32x2*)(up + (size_t)(t0 + t) * 5632) = w;
	v_fmac_f32_dpp v232, v96, v156 row_shr:2 row_mask:0xf bank_mask:0xf
	v_fmac_f32_dpp v233, v97, v157 row_shr:2 row_mask:0xf bank_mask:0xf
	v_fmac_f32_dpp v234, v84, v188 row_shr:2 row_mask:0xf bank_mask:0xf
	v_fmac_f32_dpp v235, v85, v189 row_shr:2 row_mask:0xf bank_mask:0xf
	v_fmac_f32_dpp v232, v112, v164 row_shl:15 row_mask:0xf bank_mask:0xf
	v_fmac_f32_dpp v233, v113, v165 row_shl:15 row_mask:0xf bank_mask:0xf
	v_fmac_f32_dpp v234, v100, v196 row_shl:15 row_mask:0xf bank_mask:0xf
	v_fmac_f32_dpp v235, v101, v197 row_shl:15 row_mask:0xf bank_mask:0xf
	v_fmac_f32_dpp v232, v112, v156 row_shl:14 row_mask:0xf bank_mask:0xf
	v_fmac_f32_dpp v233, v113, v157 row_shl:14 row_mask:0xf bank_mask:0xf
	v_fmac_f32_dpp v234, v100, v188 row_shl:14 row_mask:0xf bank_mask:0xf
	v_fmac_f32_dpp v235, v101, v189 row_shl:14 row_mask:0xf bank_mask:0xf
	v_mul_f32_e32 v246, v236, v232
	v_mul_f32_e32 v247, v236, v233
	v_exp_f32_e32 v246, v246
	v_exp_f32_e32 v247, v247
	s_nop 0
	v_pk_add_f32 v[246:247], v[246:247], v[238:239]
	v_rcp_f32_e32 v246, v246
	v_rcp_f32_e32 v247, v247
	v_pk_mul_f32 v[232:233], v[232:233], v[234:235]
	v_pk_mul_f32 v[232:233], v[232:233], v[246:247]
	v_cvt_pk_bf16_f32 v96, v232, v233
	v_pk_fma_f32 v[232:233], v[112:113], v[172:173], v[180:181]
	v_pk_fma_f32 v[234:235], v[100:101], v[204:205], v[212:213]
	s_nop 1
	v_fmac_f32_dpp v232, v112, v164 row_shr:1 row_mask:0xf bank_mask:0xf
	v_fmac_f32_dpp v233, v113, v165 row_shr:1 row_mask:0xf bank_mask:0xf
	v_fmac_f32_dpp v234, v100, v196 row_shr:1 row_mask:0xf bank_mask:0xf
	v_fmac_f32_dpp v235, v101, v197 row_shr:1 row_mask:0xf bank_mask:0xf
	v_fmac_f32_dpp v232, v112, v156 row_shr:2 row_mask:0xf bank_mask:0xf
	v_fmac_f32_dpp v233, v113, v157 row_shr:2 row_mask:0xf bank_mask:0xf
	v_fmac_f32_dpp v234, v100, v188 row_shr:2 row_mask:0xf bank_mask:0xf
	v_fmac_f32_dpp v235, v101, v189 row_shr:2 row_mask:0xf bank_mask:0xf
	v_fmac_f32_dpp v232, v124, v164 row_shl:15 row_mask:0xf bank_mask:0xf
	v_fmac_f32_dpp v233, v125, v165 row_shl:15 row_mask:0xf bank_mask:0xf
	v_fmac_f32_dpp v234, v116, v196 row_shl:15 row_mask:0xf bank_mask:0xf
	v_fmac_f32_dpp v235, v117, v197 row_shl:15 row_mask:0xf bank_mask:0xf
	v_fmac_f32_dpp v232, v124, v156 row_shl:14 row_mask:0xf bank_mask:0xf
	v_fmac_f32_dpp v233, v125, v157 row_shl:14 row_mask:0xf bank_mask:0xf
	v_fmac_f32_dpp v234, v116, v188 row_shl:14 row_mask:0xf bank_mask:0xf
	v_fmac_f32_dpp v235, v117, v189 row_shl:14 row_mask:0xf bank_mask:0xf
	v_mul_f32_e32 v246, v236, v232
	v_mul_f32_e32 v247, v236, v233
	v_exp_f32_e32 v246, v246
	v_exp_f32_e32 v247, v247
	s_nop 0
	v_pk_add_f32 v[246:247], v[246:247], v[238:239]
	v_rcp_f32_e32 v246, v246
	v_rcp_f32_e32 v247, v247
	v_pk_mul_f32 v[232:233], v[232:233], v[234:235]
	v_pk_mul_f32 v[232:233], v[232:233], v[246:247]
	v_cvt_pk_bf16_f32 v112, v232, v233
	v_pk_fma_f32 v[232:233], v[124:125], v[172:173], v[180:181]
	v_pk_fma_f32 v[234:235], v[116:117], v[204:205], v[212:213]
	s_nop 1
	v_fmac_f32_dpp v232, v124, v164 row_shr:1 row_mask:0xf bank_mask:0xf
	v_fmac_f32_dpp v233, v125, v165 row_shr:1 row_mask:0xf bank_mask:0xf
	v_fmac_f32_dpp v234, v116, v196 row_shr:1 row_mask:0xf bank_mask:0xf
	v_fmac_f32_dpp v235, v117, v197 row_shr:1 row_mask:0xf bank_mask:0xf
	v_fmac_f32_dpp v232, v124, v156 row_shr:2 row_mask:0xf bank_mask:0xf
	v_fmac_f32_dpp v233, v125, v157 row_shr:2 row_mask:0xf bank_mask:0xf
	v_fmac_f32_dpp v234, v116, v188 row_shr:2 row_mask:0xf bank_mask:0xf
	v_fmac_f32_dpp v235, v117, v189 row_shr:2 row_mask:0xf bank_mask:0xf
	v_mul_f32_e32 v246, v236, v232
	v_mul_f32_e32 v247, v236, v233
	v_exp_f32_e32 v246, v246
	v_exp_f32_e32 v247, v247
	s_nop 0
	v_pk_add_f32 v[246:247], v[246:247], v[238:239]
	v_rcp_f32_e32 v246, v246
	v_rcp_f32_e32 v247, v247
	v_pk_mul_f32 v[232:233], v[232:233], v[234:235]
	v_pk_mul_f32 v[232:233], v[232:233], v[246:247]
	v_cvt_pk_bf16_f32 v124, v232, v233
	v_pk_fma_f32 v[232:233], v[82:83], v[174:175], v[182:183]
	v_pk_fma_f32 v[234:235], v[70:71], v[206:207], v[214:215]
	s_nop 1
	v_fmac_f32_dpp v232, v82, v166 row_shr:1 row_mask:0xf bank_mask:0xf
	v_fmac_f32_dpp v233, v83, v167 row_shr:1 row_mask:0xf bank_mask:0xf
	v_fmac_f32_dpp v234, v70, v198 row_shr:1 row_mask:0xf bank_mask:0xf
	v_fmac_f32_dpp v235, v71, v199 row_shr:1 row_mask:0xf bank_mask:0xf
	v_fmac_f32_dpp v232, v82, v158 row_shr:2 row_mask:0xf bank_mask:0xf
	v_fmac_f32_dpp v233, v83, v159 row_shr:2 row_mask:0xf bank_mask:0xf
	v_fmac_f32_dpp v234, v70, v190 row_shr:2 row_mask:0xf bank_mask:0xf
	v_fmac_f32_dpp v235, v71, v191 row_shr:2 row_mask:0xf bank_mask:0xf
	v_fmac_f32_dpp v232, v98, v166 row_shl:15 row_mask:0xf bank_mask:0xf
	v_fmac_f32_dpp v233, v99, v167 row_shl:15 row_mask:0xf bank_mask:0xf
	v_fmac_f32_dpp v234, v86, v198 row_shl:15 row_mask:0xf bank_mask:0xf
	v_fmac_f32_dpp v235, v87, v199 row_shl:15 row_mask:0xf bank_mask:0xf
	v_fmac_f32_dpp v232, v98, v158 row_shl:14 row_mask:0xf bank_mask:0xf
	v_fmac_f32_dpp v233, v99, v159 row_shl:14 row_mask:0xf bank_mask:0xf
	v_fmac_f32_dpp v234, v86, v190 row_shl:14 row_mask:0xf bank_mask:0xf
	v_fmac_f32_dpp v235, v87, v191 row_shl:14 row_mask:0xf bank_mask:0xf
	v_mul_f32_e32 v246, v236, v232
	v_mul_f32_e32 v247, v236, v233
	v_exp_f32_e32 v246, v246
	v_exp_f32_e32 v247, v247
	s_nop 0
	v_pk_add_f32 v[246:247], v[246:247], v[238:239]
	v_rcp_f32_e32 v246, v246
	v_rcp_f32_e32 v247, v247
	v_pk_mul_f32 v[232:233], v[232:233], v[234:235]
	v_pk_mul_f32 v[232:233], v[232:233], v[246:247]
	v_cvt_pk_bf16_f32 v81, v232, v233
	v_pk_fma_f32 v[232:233], v[98:99], v[174:175], v[182:183]
	v_pk_fma_f32 v[234:235], v[86:87], v[206:207], v[214:215]
	s_nop 1
	v_fmac_f32_dpp v232, v98, v166 row_shr:1 row_mask:0xf bank_mask:0xf
; __device__ __forceinline__ unsigned cvt_pk_bf16(float lo, float hi) { unsigned r; asm("v_cvt_pk_bf16_f32 %0, %1, %2" : "=v"(r) : "v"(lo), "v"(hi)); return r; }
; __device__ __forceinline__ float sigmoid_f(float v) { return __builtin_amdgcn_rcpf(1.0f + __builtin_amdgcn_exp2f(-1.4426950409f * v)); }
; __device__ __forceinline__ f32x4 bf4(u32x2 w) { return (f32x4){bf_lo(w.x), bf_hi(w.x), bf_lo(w.y), bf_hi(w.y)}; }
; __device__ __forceinline__ void phase10(const Args& a, int G, int wv, bool dummy = false) {
;     ...
;             for (int t = 0; t < 8; ++t) { const f32x4 gc = bf4(gr[t]), vc = bf4(vr[t]);
;                 const f32x4 gg = wg0 * gm2 + wg1 * gm1 + wg2 * gc + bg, vv = wv0 * vm2 + wv1 * vm1 + wv2 * vc + bv;
;                 f32x4 o;
; #pragma unroll
;                 for (int e = 0; e < 4; ++e) o[e] = gg[e] * pg8::sigmoid_f(gg[e]) * vv[e];
;                 u32x2 w; w.x = cvt_pk_bf16(o[0], o[1]); w.y = cvt_pk_bf16(o[2], o[3]);
;                 if (dummy) *(u32x2*)((bf16_t*)(a.ws + WS_D) + ((((size_t)(row0 + t0 + t)) * 5632 + ch) & (size_t)0x1ffffff)) = w; else *(u32x2*)(up + (size_t)(t0 + t) * 5632) = w;
	v_fmac_f32_dpp v233, v99, v167 row_shr:1 row_mask:0xf bank_mask:0xf
	v_fmac_f32_dpp v234, v86, v198 row_shr:1 row_mask:0xf bank_mask:0xf
	v_fmac_f32_dpp v235, v87, v199 row_shr:1 row_mask:0xf bank_mask:0xf
	v_fmac_f32_dpp v232, v98, v158 row_shr:2 row_mask:0xf bank_mask:0xf
	v_fmac_f32_dpp v233, v99, v159 row_shr:2 row_mask:0xf bank_mask:0xf
	v_fmac_f32_dpp v234, v86, v190 row_shr:2 row_mask:0xf bank_mask:0xf
	v_fmac_f32_dpp v235, v87, v191 row_shr:2 row_mask:0xf bank_mask:0xf
	v_fmac_f32_dpp v232, v114, v166 row_shl:15 row_mask:0xf bank_mask:0xf
	v_fmac_f32_dpp v233, v115, v167 row_shl:15 row_mask:0xf bank_mask:0xf
	v_fmac_f32_dpp v234, v102, v198 row_shl:15 row_mask:0xf bank_mask:0xf
	v_fmac_f32_dpp v235, v103, v199 row_shl:15 row_mask:0xf bank_mask:0xf
	v_fmac_f32_dpp v232, v114, v158 row_shl:14 row_mask:0xf bank_mask:0xf
	v_fmac_f32_dpp v233, v115, v159 row_shl:14 row_mask:0xf bank_mask:0xf
	v_fmac_f32_dpp v234, v102, v190 row_shl:14 row_mask:0xf bank_mask:0xf
	v_fmac_f32_dpp v235, v103, v191 row_shl:14 row_mask:0xf bank_mask:0xf
	v_mul_f32_e32 v246, v236, v232
	v_mul_f32_e32 v247, v236, v233
	v_exp_f32_e32 v246, v246
	v_exp_f32_e32 v247, v247
	s_nop 0
	v_pk_add_f32 v[246:247], v[246:247], v[238:239]
	v_rcp_f32_e32 v246, v246
	v_rcp_f32_e32 v247, v247
	v_pk_mul_f32 v[232:233], v[232:233], v[234:235]
	v_pk_mul_f32 v[232:233], v[232:233], v[246:247]
	v_cvt_pk_bf16_f32 v97, v232, v233
	v_pk_fma_f32 v[232:233], v[114:115], v[174:175], v[182:183]
	v_pk_fma_f32 v[234:235], v[102:103], v[206:207], v[214:215]
	s_nop 1
	v_fmac_f32_dpp v232, v114, v166 row_shr:1 row_mask:0xf bank_mask:0xf
	v_fmac_f32_dpp v233, v115, v167 row_shr:1 row_mask:0xf bank_mask:0xf
	v_fmac_f32_dpp v234, v102, v198 row_shr:1 row_mask:0xf bank_mask:0xf
	v_fmac_f32_dpp v235, v103, v199 row_shr:1 row_mask:0xf bank_mask:0xf
	v_fmac_f32_dpp v232, v114, v158 row_shr:2 row_mask:0xf bank_mask:0xf
	v_fmac_f32_dpp v233, v115, v159 row_shr:2 row_mask:0xf bank_mask:0xf
	v_fmac_f32_dpp v234, v102, v190 row_shr:2 row_mask:0xf bank_mask:0xf
	v_fmac_f32_dpp v235, v103, v191 row_shr:2 row_mask:0xf bank_mask:0xf
	v_fmac_f32_dpp v232, v126, v166 row_shl:15 row_mask:0xf bank_mask:0xf
	v_fmac_f32_dpp v233, v127, v167 row_shl:15 row_mask:0xf bank_mask:0xf
	v_fmac_f32_dpp v234, v118, v198 row_shl:15 row_mask:0xf bank_mask:0xf
	v_fmac_f32_dpp v235, v119, v199 row_shl:15 row_mask:0xf bank_mask:0xf
	v_fmac_f32_dpp v232, v126, v158 row_shl:14 row_mask:0xf bank_mask:0xf
	v_fmac_f32_dpp v233, v127, v159 row_shl:14 row_mask:0xf bank_mask:0xf
	v_fmac_f32_dpp v234, v118, v190 row_shl:14 row_mask:0xf bank_mask:0xf
	v_fmac_f32_dpp v235, v119, v191 row_shl:14 row_mask:0xf bank_mask:0xf
	v_mul_f32_e32 v246, v236, v232
	v_mul_f32_e32 v247, v236, v233
	v_exp_f32_e32 v246, v246
	v_exp_f32_e32 v247, v247
	s_nop 0
	v_pk_add_f32 v[246:247], v[246:247], v[238:239]
	v_rcp_f32_e32 v246, v246
	v_rcp_f32_e32 v247, v247
	v_pk_mul_f32 v[232:233], v[232:233], v[234:235]
	v_pk_mul_f32 v[232:233], v[232:233], v[246:247]
	v_cvt_pk_bf16_f32 v113, v232, v233
	v_pk_fma_f32 v[232:233], v[126:127], v[174:175], v[182:183]
	v_pk_fma_f32 v[234:235], v[118:119], v[206:207], v[214:215]
	s_nop 1
	v_fmac_f32_dpp v232, v126, v166 row_shr:1 row_mask:0xf bank_mask:0xf
	v_fmac_f32_dpp v233, v127, v167 row_shr:1 row_mask:0xf bank_mask:0xf
	v_fmac_f32_dpp v234, v118, v198 row_shr:1 row_mask:0xf bank_mask:0xf
	v_fmac_f32_dpp v235, v119, v199 row_shr:1 row_mask:0xf bank_mask:0xf
	v_fmac_f32_dpp v232, v126, v158 row_shr:2 row_mask:0xf bank_mask:0xf
	v_fmac_f32_dpp v233, v127, v159 row_shr:2 row_mask:0xf bank_mask:0xf
	v_fmac_f32_dpp v234, v118, v190 row_shr:2 row_mask:0xf bank_mask:0xf
	v_fmac_f32_dpp v235, v119, v191 row_shr:2 row_mask:0xf bank_mask:0xf
	v_mul_f32_e32 v246, v236, v232
	v_mul_f32_e32 v247, v236, v233
	v_exp_f32_e32 v246, v246
	v_exp_f32_e32 v247, v247
	s_nop 0
	v_pk_add_f32 v[246:247], v[246:247], v[238:239]
	v_rcp_f32_e32 v246, v246
	v_rcp_f32_e32 v247, v247
	v_pk_mul_f32 v[232:233], v[232:233], v[234:235]
	v_pk_mul_f32 v[232:233], v[232:233], v[246:247]
	v_cvt_pk_bf16_f32 v125, v232, v233
	v_pk_fma_f32 v[232:233], v[72:73], v[176:177], v[184:185]
	v_pk_fma_f32 v[234:235], v[64:65], v[208:209], v[216:217]
	s_nop 1
	v_fmac_f32_dpp v232, v72, v168 row_shr:1 row_mask:0xf bank_mask:0xf
	v_fmac_f32_dpp v233, v73, v169 row_shr:1 row_mask:0xf bank_mask:0xf
	v_fmac_f32_dpp v234, v64, v200 row_shr:1 row_mask:0xf bank_mask:0xf
	v_fmac_f32_dpp v235, v65, v201 row_shr:1 row_mask:0xf bank_mask:0xf
	v_fmac_f32_dpp v232, v72, v160 row_shr:2 row_mask:0xf bank_mask:0xf
	v_fmac_f32_dpp v233, v73, v161 row_shr:2 row_mask:0xf bank_mask:0xf
	v_fmac_f32_dpp v234, v64, v192 row_shr:2 row_mask:0xf bank_mask:0xf
	v_fmac_f32_dpp v235, v65, v193 row_shr:2 row_mask:0xf bank_mask:0xf
	v_fmac_f32_dpp v232, v88, v168 row_shl:15 row_mask:0xf bank_mask:0xf
	v_fmac_f32_dpp v233, v89, v169 row_shl:15 row_mask:0xf bank_mask:0xf
	v_fmac_f32_dpp v234, v76, v200 row_shl:15 row_mask:0xf bank_mask:0xf
	v_fmac_f32_dpp v235, v77, v201 row_shl:15 row_mask:0xf bank_mask:0xf
	v_fmac_f32_dpp v232, v88, v160 row_shl:14 row_mask:0xf bank_mask:0xf
	v_fmac_f32_dpp v233, v89, v161 row_shl:14 row_mask:0xf bank_mask:0xf
	v_fmac_f32_dpp v234, v76, v192 row_shl:14 row_mask:0xf bank_mask:0xf
	v_fmac_f32_dpp v235, v77, v193 row_shl:14 row_mask:0xf bank_mask:0xf
	v_mul_f32_e32 v246, v236, v232
	v_mul_f32_e32 v247, v236, v233
	v_exp_f32_e32 v246, v246
	v_exp_f32_e32 v247, v247
	s_nop 0
	v_pk_add_f32 v[246:247], v[246:247], v[238:239]
	v_rcp_f32_e32 v246, v246
	v_rcp_f32_e32 v247, v247
	v_pk_mul_f32 v[232:233], v[232:233], v[234:235]
	v_pk_mul_f32 v[232:233], v[232:233], v[246:247]
; __device__ __forceinline__ unsigned cvt_pk_bf16(float lo, float hi) { unsigned r; asm("v_cvt_pk_bf16_f32 %0, %1, %2" : "=v"(r) : "v"(lo), "v"(hi)); return r; }
; __device__ __forceinline__ float sigmoid_f(float v) { return __builtin_amdgcn_rcpf(1.0f + __builtin_amdgcn_exp2f(-1.4426950409f * v)); }
; __device__ __forceinline__ f32x4 bf4(u32x2 w) { return (f32x4){bf_lo(w.x), bf_hi(w.x), bf_lo(w.y), bf_hi(w.y)}; }
; __device__ __forceinline__ void phase10(const Args& a, int G, int wv, bool dummy = false) {
;     ...
;             for (int t = 0; t < 8; ++t) { const f32x4 gc = bf4(gr[t]), vc = bf4(vr[t]);
;                 const f32x4 gg = wg0 * gm2 + wg1 * gm1 + wg2 * gc + bg, vv = wv0 * vm2 + wv1 * vm1 + wv2 * vc + bv;
;                 f32x4 o;
; #pragma unroll
;                 for (int e = 0; e < 4; ++e) o[e] = gg[e] * pg8::sigmoid_f(gg[e]) * vv[e];
;                 u32x2 w; w.x = cvt_pk_bf16(o[0], o[1]); w.y = cvt_pk_bf16(o[2], o[3]);
;                 if (dummy) *(u32x2*)((bf16_t*)(a.ws + WS_D) + ((((size_t)(row0 + t0 + t)) * 5632 + ch) & (size_t)0x1ffffff)) = w; else *(u32x2*)(up + (size_t)(t0 + t) * 5632) = w;
	v_cvt_pk_bf16_f32 v82, v232, v233
	v_pk_fma_f32 v[232:233], v[88:89], v[176:177], v[184:185]
	v_pk_fma_f32 v[234:235], v[76:77], v[208:209], v[216:217]
	s_nop 1
	v_fmac_f32_dpp v232, v88, v168 row_shr:1 row_mask:0xf bank_mask:0xf
	v_fmac_f32_dpp v233, v89, v169 row_shr:1 row_mask:0xf bank_mask:0xf
	v_fmac_f32_dpp v234, v76, v200 row_shr:1 row_mask:0xf bank_mask:0xf
	v_fmac_f32_dpp v235, v77, v201 row_shr:1 row_mask:0xf bank_mask:0xf
	v_fmac_f32_dpp v232, v88, v160 row_shr:2 row_mask:0xf bank_mask:0xf
	v_fmac_f32_dpp v233, v89, v161 row_shr:2 row_mask:0xf bank_mask:0xf
	v_fmac_f32_dpp v234, v76, v192 row_shr:2 row_mask:0xf bank_mask:0xf
	v_fmac_f32_dpp v235, v77, v193 row_shr:2 row_mask:0xf bank_mask:0xf
	v_fmac_f32_dpp v232, v104, v168 row_shl:15 row_mask:0xf bank_mask:0xf
	v_fmac_f32_dpp v233, v105, v169 row_shl:15 row_mask:0xf bank_mask:0xf
	v_fmac_f32_dpp v234, v92, v200 row_shl:15 row_mask:0xf bank_mask:0xf
	v_fmac_f32_dpp v235, v93, v201 row_shl:15 row_mask:0xf bank_mask:0xf
	v_fmac_f32_dpp v232, v104, v160 row_shl:14 row_mask:0xf bank_mask:0xf
	v_fmac_f32_dpp v233, v105, v161 row_shl:14 row_mask:0xf bank_mask:0xf
	v_fmac_f32_dpp v234, v92, v192 row_shl:14 row_mask:0xf bank_mask:0xf
	v_fmac_f32_dpp v235, v93, v193 row_shl:14 row_mask:0xf bank_mask:0xf
	v_mul_f32_e32 v246, v236, v232
	v_mul_f32_e32 v247, v236, v233
	v_exp_f32_e32 v246, v246
	v_exp_f32_e32 v247, v247
	s_nop 0
	v_pk_add_f32 v[246:247], v[246:247], v[238:239]
	v_rcp_f32_e32 v246, v246
	v_rcp_f32_e32 v247, v247
	v_pk_mul_f32 v[232:233], v[232:233], v[234:235]
	v_pk_mul_f32 v[232:233], v[232:233], v[246:247]
	v_cvt_pk_bf16_f32 v98, v232, v233
	v_pk_fma_f32 v[232:233], v[104:105], v[176:177], v[184:185]
	v_pk_fma_f32 v[234:235], v[92:93], v[208:209], v[216:217]
	s_nop 1
	v_fmac_f32_dpp v232, v104, v168 row_shr:1 row_mask:0xf bank_mask:0xf
	v_fmac_f32_dpp v233, v105, v169 row_shr:1 row_mask:0xf bank_mask:0xf
	v_fmac_f32_dpp v234, v92, v200 row_shr:1 row_mask:0xf bank_mask:0xf
	v_fmac_f32_dpp v235, v93, v201 row_shr:1 row_mask:0xf bank_mask:0xf
	v_fmac_f32_dpp v232, v104, v160 row_shr:2 row_mask:0xf bank_mask:0xf
	v_fmac_f32_dpp v233, v105, v161 row_shr:2 row_mask:0xf bank_mask:0xf
	v_fmac_f32_dpp v234, v92, v192 row_shr:2 row_mask:0xf bank_mask:0xf
	v_fmac_f32_dpp v235, v93, v193 row_shr:2 row_mask:0xf bank_mask:0xf
	v_fmac_f32_dpp v232, v120, v168 row_shl:15 row_mask:0xf bank_mask:0xf
	v_fmac_f32_dpp v233, v121, v169 row_shl:15 row_mask:0xf bank_mask:0xf
	v_fmac_f32_dpp v234, v108, v200 row_shl:15 row_mask:0xf bank_mask:0xf
	v_fmac_f32_dpp v235, v109, v201 row_shl:15 row_mask:0xf bank_mask:0xf
	v_fmac_f32_dpp v232, v120, v160 row_shl:14 row_mask:0xf bank_mask:0xf
	v_fmac_f32_dpp v233, v121, v161 row_shl:14 row_mask:0xf bank_mask:0xf
	v_fmac_f32_dpp v234, v108, v192 row_shl:14 row_mask:0xf bank_mask:0xf
	v_fmac_f32_dpp v235, v109, v193 row_shl:14 row_mask:0xf bank_mask:0xf
	v_mul_f32_e32 v246, v236, v232
	v_mul_f32_e32 v247, v236, v233
	v_exp_f32_e32 v246, v246
	v_exp_f32_e32 v247, v247
	s_nop 0
	v_pk_add_f32 v[246:247], v[246:247], v[238:239]
	v_rcp_f32_e32 v246, v246
	v_rcp_f32_e32 v247, v247
	v_pk_mul_f32 v[232:233], v[232:233], v[234:235]
	v_pk_mul_f32 v[232:233], v[232:233], v[246:247]
	v_cvt_pk_bf16_f32 v114, v232, v233
	v_pk_fma_f32 v[232:233], v[120:121], v[176:177], v[184:185]
	v_pk_fma_f32 v[234:235], v[108:109], v[208:209], v[216:217]
	s_nop 1
	v_fmac_f32_dpp v232, v120, v168 row_shr:1 row_mask:0xf bank_mask:0xf
	v_fmac_f32_dpp v233, v121, v169 row_shr:1 row_mask:0xf bank_mask:0xf
	v_fmac_f32_dpp v234, v108, v200 row_shr:1 row_mask:0xf bank_mask:0xf
	v_fmac_f32_dpp v235, v109, v201 row_shr:1 row_mask:0xf bank_mask:0xf
	v_fmac_f32_dpp v232, v120, v160 row_shr:2 row_mask:0xf bank_mask:0xf
	v_fmac_f32_dpp v233, v121, v161 row_shr:2 row_mask:0xf bank_mask:0xf
	v_fmac_f32_dpp v234, v108, v192 row_shr:2 row_mask:0xf bank_mask:0xf
	v_fmac_f32_dpp v235, v109, v193 row_shr:2 row_mask:0xf bank_mask:0xf
	v_mul_f32_e32 v246, v236, v232
	v_mul_f32_e32 v247, v236, v233
	v_exp_f32_e32 v246, v246
	v_exp_f32_e32 v247, v247
	s_nop 0
	v_pk_add_f32 v[246:247], v[246:247], v[238:239]
	v_rcp_f32_e32 v246, v246
	v_rcp_f32_e32 v247, v247
	v_pk_mul_f32 v[232:233], v[232:233], v[234:235]
	v_pk_mul_f32 v[232:233], v[232:233], v[246:247]
	v_cvt_pk_bf16_f32 v126, v232, v233
	v_pk_fma_f32 v[232:233], v[74:75], v[178:179], v[186:187]
	v_pk_fma_f32 v[234:235], v[66:67], v[210:211], v[218:219]
	s_nop 1
	v_fmac_f32_dpp v232, v74, v170 row_shr:1 row_mask:0xf bank_mask:0xf
	v_fmac_f32_dpp v233, v75, v171 row_shr:1 row_mask:0xf bank_mask:0xf
	v_fmac_f32_dpp v234, v66, v202 row_shr:1 row_mask:0xf bank_mask:0xf
	v_fmac_f32_dpp v235, v67, v203 row_shr:1 row_mask:0xf bank_mask:0xf
	v_fmac_f32_dpp v232, v74, v162 row_shr:2 row_mask:0xf bank_mask:0xf
	v_fmac_f32_dpp v233, v75, v163 row_shr:2 row_mask:0xf bank_mask:0xf
	v_fmac_f32_dpp v234, v66, v194 row_shr:2 row_mask:0xf bank_mask:0xf
	v_fmac_f32_dpp v235, v67, v195 row_shr:2 row_mask:0xf bank_mask:0xf
	v_fmac_f32_dpp v232, v90, v170 row_shl:15 row_mask:0xf bank_mask:0xf
	v_fmac_f32_dpp v233, v91, v171 row_shl:15 row_mask:0xf bank_mask:0xf
	v_fmac_f32_dpp v234, v78, v202 row_shl:15 row_mask:0xf bank_mask:0xf
	v_fmac_f32_dpp v235, v79, v203 row_shl:15 row_mask:0xf bank_mask:0xf
	v_fmac_f32_dpp v232, v90, v162 row_shl:14 row_mask:0xf bank_mask:0xf
	v_fmac_f32_dpp v233, v91, v163 row_shl:14 row_mask:0xf bank_mask:0xf
	v_fmac_f32_dpp v234, v78, v194 row_shl:14 row_mask:0xf bank_mask:0xf
	v_fmac_f32_dpp v235, v79, v195 row_shl:14 row_mask:0xf bank_mask:0xf
	v_mul_f32_e32 v246, v236, v232
	v_mul_f32_e32 v247, v236, v233
	v_exp_f32_e32 v246, v246
; __device__ __forceinline__ unsigned cvt_pk_bf16(float lo, float hi) { unsigned r; asm("v_cvt_pk_bf16_f32 %0, %1, %2" : "=v"(r) : "v"(lo), "v"(hi)); return r; }
; __device__ __forceinline__ float sigmoid_f(float v) { return __builtin_amdgcn_rcpf(1.0f + __builtin_amdgcn_exp2f(-1.4426950409f * v)); }
; __device__ __forceinline__ u32x4 pack8(f32x4 a, f32x4 b) { u32x4 w; w.x = cvt_pk_bf16(a[0], a[1]); w.y = cvt_pk_bf16(a[2], a[3]); w.z = cvt_pk_bf16(b[0], b[1]); w.w = cvt_pk_bf16(b[2], b[3]); return w; }
; __device__ __forceinline__ f32x4 bf4(u32x2 w) { return (f32x4){bf_lo(w.x), bf_hi(w.x), bf_lo(w.y), bf_hi(w.y)}; }
;     __device__ __forceinline__ void operator()(const f32x4 (&acc)[2][2][4][2], const Unit& u, int wr, int wc, int fr, int fq) const {
;     ...
;             for (int m = 0; m < 4; ++m) { const int row = row0 + ai * HALF + m * 16; bf16_t* rowp = UP + (size_t)row * 5632 + u.pn * HALF + wc * 32 + 8 * fq;
; #pragma unroll
;                 for (int bj = 0; bj < 2; ++bj) { const u32x4 w = pack8(acc[ai][bj][m][0], acc[ai][bj][m][1]); __builtin_nontemporal_store(w, (u32x4*)(rowp + (size_t)bj * ((size_t)16384 * 5632)));
; __device__ __forceinline__ void phase10(const Args& a, int G, int wv, bool dummy = false) {
;     ...
;             for (int t = 0; t < 8; ++t) { const f32x4 gc = bf4(gr[t]), vc = bf4(vr[t]);
;                 const f32x4 gg = wg0 * gm2 + wg1 * gm1 + wg2 * gc + bg, vv = wv0 * vm2 + wv1 * vm1 + wv2 * vc + bv;
;                 f32x4 o;
; #pragma unroll
;                 for (int e = 0; e < 4; ++e) o[e] = gg[e] * pg8::sigmoid_f(gg[e]) * vv[e];
;                 u32x2 w; w.x = cvt_pk_bf16(o[0], o[1]); w.y = cvt_pk_bf16(o[2], o[3]);
;                 if (dummy) *(u32x2*)((bf16_t*)(a.ws + WS_D) + ((((size_t)(row0 + t0 + t)) * 5632 + ch) & (size_t)0x1ffffff)) = w; else *(u32x2*)(up + (size_t)(t0 + t) * 5632) = w;
	v_exp_f32_e32 v247, v247
	s_nop 0
	v_pk_add_f32 v[246:247], v[246:247], v[238:239]
	v_rcp_f32_e32 v246, v246
	v_rcp_f32_e32 v247, v247
	v_pk_mul_f32 v[232:233], v[232:233], v[234:235]
	v_pk_mul_f32 v[232:233], v[232:233], v[246:247]
	v_cvt_pk_bf16_f32 v83, v232, v233
	v_pk_fma_f32 v[232:233], v[90:91], v[178:179], v[186:187]
	v_pk_fma_f32 v[234:235], v[78:79], v[210:211], v[218:219]
	s_nop 1
	v_fmac_f32_dpp v232, v90, v170 row_shr:1 row_mask:0xf bank_mask:0xf
	v_fmac_f32_dpp v233, v91, v171 row_shr:1 row_mask:0xf bank_mask:0xf
	v_fmac_f32_dpp v234, v78, v202 row_shr:1 row_mask:0xf bank_mask:0xf
	v_fmac_f32_dpp v235, v79, v203 row_shr:1 row_mask:0xf bank_mask:0xf
	v_fmac_f32_dpp v232, v90, v162 row_shr:2 row_mask:0xf bank_mask:0xf
	v_fmac_f32_dpp v233, v91, v163 row_shr:2 row_mask:0xf bank_mask:0xf
	v_fmac_f32_dpp v234, v78, v194 row_shr:2 row_mask:0xf bank_mask:0xf
	v_fmac_f32_dpp v235, v79, v195 row_shr:2 row_mask:0xf bank_mask:0xf
	v_fmac_f32_dpp v232, v106, v170 row_shl:15 row_mask:0xf bank_mask:0xf
	v_fmac_f32_dpp v233, v107, v171 row_shl:15 row_mask:0xf bank_mask:0xf
	v_fmac_f32_dpp v234, v94, v202 row_shl:15 row_mask:0xf bank_mask:0xf
	v_fmac_f32_dpp v235, v95, v203 row_shl:15 row_mask:0xf bank_mask:0xf
	v_fmac_f32_dpp v232, v106, v162 row_shl:14 row_mask:0xf bank_mask:0xf
	v_fmac_f32_dpp v233, v107, v163 row_shl:14 row_mask:0xf bank_mask:0xf
	v_fmac_f32_dpp v234, v94, v194 row_shl:14 row_mask:0xf bank_mask:0xf
	v_fmac_f32_dpp v235, v95, v195 row_shl:14 row_mask:0xf bank_mask:0xf
	v_mul_f32_e32 v246, v236, v232
	v_mul_f32_e32 v247, v236, v233
	v_exp_f32_e32 v246, v246
	v_exp_f32_e32 v247, v247
	s_nop 0
	v_pk_add_f32 v[246:247], v[246:247], v[238:239]
	v_rcp_f32_e32 v246, v246
	v_rcp_f32_e32 v247, v247
	v_pk_mul_f32 v[232:233], v[232:233], v[234:235]
	v_pk_mul_f32 v[232:233], v[232:233], v[246:247]
	v_cvt_pk_bf16_f32 v99, v232, v233
	v_pk_fma_f32 v[232:233], v[106:107], v[178:179], v[186:187]
	v_pk_fma_f32 v[234:235], v[94:95], v[210:211], v[218:219]
	s_nop 1
	v_fmac_f32_dpp v232, v106, v170 row_shr:1 row_mask:0xf bank_mask:0xf
	v_fmac_f32_dpp v233, v107, v171 row_shr:1 row_mask:0xf bank_mask:0xf
	v_fmac_f32_dpp v234, v94, v202 row_shr:1 row_mask:0xf bank_mask:0xf
	v_fmac_f32_dpp v235, v95, v203 row_shr:1 row_mask:0xf bank_mask:0xf
	v_fmac_f32_dpp v232, v106, v162 row_shr:2 row_mask:0xf bank_mask:0xf
	v_fmac_f32_dpp v233, v107, v163 row_shr:2 row_mask:0xf bank_mask:0xf
	v_fmac_f32_dpp v234, v94, v194 row_shr:2 row_mask:0xf bank_mask:0xf
	v_fmac_f32_dpp v235, v95, v195 row_shr:2 row_mask:0xf bank_mask:0xf
	v_fmac_f32_dpp v232, v122, v170 row_shl:15 row_mask:0xf bank_mask:0xf
	v_fmac_f32_dpp v233, v123, v171 row_shl:15 row_mask:0xf bank_mask:0xf
	v_fmac_f32_dpp v234, v110, v202 row_shl:15 row_mask:0xf bank_mask:0xf
	v_fmac_f32_dpp v235, v111, v203 row_shl:15 row_mask:0xf bank_mask:0xf
	v_fmac_f32_dpp v232, v122, v162 row_shl:14 row_mask:0xf bank_mask:0xf
	v_fmac_f32_dpp v233, v123, v163 row_shl:14 row_mask:0xf bank_mask:0xf
	v_fmac_f32_dpp v234, v110, v194 row_shl:14 row_mask:0xf bank_mask:0xf
	v_fmac_f32_dpp v235, v111, v195 row_shl:14 row_mask:0xf bank_mask:0xf
	v_mul_f32_e32 v246, v236, v232
	v_mul_f32_e32 v247, v236, v233
	v_exp_f32_e32 v246, v246
	v_exp_f32_e32 v247, v247
	s_nop 0
	v_pk_add_f32 v[246:247], v[246:247], v[238:239]
	v_rcp_f32_e32 v246, v246
	v_rcp_f32_e32 v247, v247
	v_pk_mul_f32 v[232:233], v[232:233], v[234:235]
	v_pk_mul_f32 v[232:233], v[232:233], v[246:247]
	v_cvt_pk_bf16_f32 v115, v232, v233
	v_pk_fma_f32 v[232:233], v[122:123], v[178:179], v[186:187]
	v_pk_fma_f32 v[234:235], v[110:111], v[210:211], v[218:219]
	s_nop 1
	v_fmac_f32_dpp v232, v122, v170 row_shr:1 row_mask:0xf bank_mask:0xf
	v_fmac_f32_dpp v233, v123, v171 row_shr:1 row_mask:0xf bank_mask:0xf
	v_fmac_f32_dpp v234, v110, v202 row_shr:1 row_mask:0xf bank_mask:0xf
	v_fmac_f32_dpp v235, v111, v203 row_shr:1 row_mask:0xf bank_mask:0xf
	v_fmac_f32_dpp v232, v122, v162 row_shr:2 row_mask:0xf bank_mask:0xf
	v_fmac_f32_dpp v233, v123, v163 row_shr:2 row_mask:0xf bank_mask:0xf
	v_fmac_f32_dpp v234, v110, v194 row_shr:2 row_mask:0xf bank_mask:0xf
	v_fmac_f32_dpp v235, v111, v195 row_shr:2 row_mask:0xf bank_mask:0xf
	v_mul_f32_e32 v246, v236, v232
	v_mul_f32_e32 v247, v236, v233
	v_exp_f32_e32 v246, v246
	v_exp_f32_e32 v247, v247
	s_nop 0
	v_pk_add_f32 v[246:247], v[246:247], v[238:239]
	v_rcp_f32_e32 v246, v246
	v_rcp_f32_e32 v247, v247
	v_pk_mul_f32 v[232:233], v[232:233], v[234:235]
	v_pk_mul_f32 v[232:233], v[232:233], v[246:247]
	v_cvt_pk_bf16_f32 v127, v232, v233
	s_andn2_b64 exec, exec, s[64:65]
	global_store_dwordx4 v149, v[124:127], s[100:101] sc1
	s_mov_b64 exec, -1
	s_add_u32 s36, s100, 0x2c000
	s_addc_u32 s37, s101, 0
	global_store_dwordx4 v149, v[112:115], s[36:37] sc1
	s_add_u32 s36, s100, 0x58000
	s_addc_u32 s37, s101, 0
	global_store_dwordx4 v149, v[96:99], s[36:37] sc1
	s_add_u32 s36, s100, 0x84000
	s_addc_u32 s37, s101, 0
	global_store_dwordx4 v149, v[80:83], s[36:37] sc1
	s_nop 4
	v_pk_fma_f32 v[232:233], v[16:17], v[172:173], v[180:181]
	v_pk_fma_f32 v[234:235], v[4:5], v[204:205], v[212:213]
	s_nop 1
	v_fmac_f32_dpp v232, v16, v164 row_shr:1 row_mask:0xf bank_mask:0xf
	v_fmac_f32_dpp v233, v17, v165 row_shr:1 row_mask:0xf bank_mask:0xf
	v_fmac_f32_dpp v234, v4, v196 row_shr:1 row_mask:0xf bank_mask:0xf
	v_fmac_f32_dpp v235, v5, v197 row_shr:1 row_mask:0xf bank_mask:0xf
	v_fmac_f32_dpp v232, v16, v156 row_shr:2 row_mask:0xf bank_mask:0xf
	v_fmac_f32_dpp v233, v17, v157 row_shr:2 row_mask:0xf bank_mask:0xf
	v_fmac_f32_dpp v234, v4, v188 row_shr:2 row_mask:0xf bank_mask:0xf
	v_fmac_f32_dpp v235, v5, v189 row_shr:2 row_mask:0xf bank_mask:0xf
; __device__ __forceinline__ unsigned cvt_pk_bf16(float lo, float hi) { unsigned r; asm("v_cvt_pk_bf16_f32 %0, %1, %2" : "=v"(r) : "v"(lo), "v"(hi)); return r; }
; __device__ __forceinline__ float sigmoid_f(float v) { return __builtin_amdgcn_rcpf(1.0f + __builtin_amdgcn_exp2f(-1.4426950409f * v)); }
; __device__ __forceinline__ f32x4 bf4(u32x2 w) { return (f32x4){bf_lo(w.x), bf_hi(w.x), bf_lo(w.y), bf_hi(w.y)}; }
; __device__ __forceinline__ void phase10(const Args& a, int G, int wv, bool dummy = false) {
;     ...
;             for (int t = 0; t < 8; ++t) { const f32x4 gc = bf4(gr[t]), vc = bf4(vr[t]);
;                 const f32x4 gg = wg0 * gm2 + wg1 * gm1 + wg2 * gc + bg, vv = wv0 * vm2 + wv1 * vm1 + wv2 * vc + bv;
;                 f32x4 o;
; #pragma unroll
;                 for (int e = 0; e < 4; ++e) o[e] = gg[e] * pg8::sigmoid_f(gg[e]) * vv[e];
;                 u32x2 w; w.x = cvt_pk_bf16(o[0], o[1]); w.y = cvt_pk_bf16(o[2], o[3]);
;                 if (dummy) *(u32x2*)((bf16_t*)(a.ws + WS_D) + ((((size_t)(row0 + t0 + t)) * 5632 + ch) & (size_t)0x1ffffff)) = w; else *(u32x2*)(up + (size_t)(t0 + t) * 5632) = w;
	v_fmac_f32_dpp v232, v32, v164 row_shl:15 row_mask:0xf bank_mask:0xf
	v_fmac_f32_dpp v233, v33, v165 row_shl:15 row_mask:0xf bank_mask:0xf
	v_fmac_f32_dpp v234, v20, v196 row_shl:15 row_mask:0xf bank_mask:0xf
	v_fmac_f32_dpp v235, v21, v197 row_shl:15 row_mask:0xf bank_mask:0xf
	v_fmac_f32_dpp v232, v32, v156 row_shl:14 row_mask:0xf bank_mask:0xf
	v_fmac_f32_dpp v233, v33, v157 row_shl:14 row_mask:0xf bank_mask:0xf
	v_fmac_f32_dpp v234, v20, v188 row_shl:14 row_mask:0xf bank_mask:0xf
	v_fmac_f32_dpp v235, v21, v189 row_shl:14 row_mask:0xf bank_mask:0xf
	v_mul_f32_e32 v246, v236, v232
	v_mul_f32_e32 v247, v236, v233
	v_exp_f32_e32 v246, v246
	v_exp_f32_e32 v247, v247
	s_nop 0
	v_pk_add_f32 v[246:247], v[246:247], v[238:239]
	v_rcp_f32_e32 v246, v246
	v_rcp_f32_e32 v247, v247
	v_pk_mul_f32 v[232:233], v[232:233], v[234:235]
	v_pk_mul_f32 v[232:233], v[232:233], v[246:247]
	v_cvt_pk_bf16_f32 v16, v232, v233
	v_pk_fma_f32 v[232:233], v[32:33], v[172:173], v[180:181]
	v_pk_fma_f32 v[234:235], v[20:21], v[204:205], v[212:213]
	s_nop 1
	v_fmac_f32_dpp v232, v32, v164 row_shr:1 row_mask:0xf bank_mask:0xf
	v_fmac_f32_dpp v233, v33, v165 row_shr:1 row_mask:0xf bank_mask:0xf
	v_fmac_f32_dpp v234, v20, v196 row_shr:1 row_mask:0xf bank_mask:0xf
	v_fmac_f32_dpp v235, v21, v197 row_shr:1 row_mask:0xf bank_mask:0xf
	v_fmac_f32_dpp v232, v32, v156 row_shr:2 row_mask:0xf bank_mask:0xf
	v_fmac_f32_dpp v233, v33, v157 row_shr:2 row_mask:0xf bank_mask:0xf
	v_fmac_f32_dpp v234, v20, v188 row_shr:2 row_mask:0xf bank_mask:0xf
	v_fmac_f32_dpp v235, v21, v189 row_shr:2 row_mask:0xf bank_mask:0xf
	v_fmac_f32_dpp v232, v48, v164 row_shl:15 row_mask:0xf bank_mask:0xf
	v_fmac_f32_dpp v233, v49, v165 row_shl:15 row_mask:0xf bank_mask:0xf
	v_fmac_f32_dpp v234, v36, v196 row_shl:15 row_mask:0xf bank_mask:0xf
	v_fmac_f32_dpp v235, v37, v197 row_shl:15 row_mask:0xf bank_mask:0xf
	v_fmac_f32_dpp v232, v48, v156 row_shl:14 row_mask:0xf bank_mask:0xf
	v_fmac_f32_dpp v233, v49, v157 row_shl:14 row_mask:0xf bank_mask:0xf
	v_fmac_f32_dpp v234, v36, v188 row_shl:14 row_mask:0xf bank_mask:0xf
	v_fmac_f32_dpp v235, v37, v189 row_shl:14 row_mask:0xf bank_mask:0xf
	v_mul_f32_e32 v246, v236, v232
	v_mul_f32_e32 v247, v236, v233
	v_exp_f32_e32 v246, v246
	v_exp_f32_e32 v247, v247
	s_nop 0
	v_pk_add_f32 v[246:247], v[246:247], v[238:239]
	v_rcp_f32_e32 v246, v246
	v_rcp_f32_e32 v247, v247
	v_pk_mul_f32 v[232:233], v[232:233], v[234:235]
	v_pk_mul_f32 v[232:233], v[232:233], v[246:247]
	v_cvt_pk_bf16_f32 v32, v232, v233
	v_pk_fma_f32 v[232:233], v[48:49], v[172:173], v[180:181]
	v_pk_fma_f32 v[234:235], v[36:37], v[204:205], v[212:213]
	s_nop 1
	v_fmac_f32_dpp v232, v48, v164 row_shr:1 row_mask:0xf bank_mask:0xf
	v_fmac_f32_dpp v233, v49, v165 row_shr:1 row_mask:0xf bank_mask:0xf
	v_fmac_f32_dpp v234, v36, v196 row_shr:1 row_mask:0xf bank_mask:0xf
	v_fmac_f32_dpp v235, v37, v197 row_shr:1 row_mask:0xf bank_mask:0xf
	v_fmac_f32_dpp v232, v48, v156 row_shr:2 row_mask:0xf bank_mask:0xf
	v_fmac_f32_dpp v233, v49, v157 row_shr:2 row_mask:0xf bank_mask:0xf
	v_fmac_f32_dpp v234, v36, v188 row_shr:2 row_mask:0xf bank_mask:0xf
	v_fmac_f32_dpp v235, v37, v189 row_shr:2 row_mask:0xf bank_mask:0xf
	v_fmac_f32_dpp v232, v60, v164 row_shl:15 row_mask:0xf bank_mask:0xf
	v_fmac_f32_dpp v233, v61, v165 row_shl:15 row_mask:0xf bank_mask:0xf
	v_fmac_f32_dpp v234, v52, v196 row_shl:15 row_mask:0xf bank_mask:0xf
	v_fmac_f32_dpp v235, v53, v197 row_shl:15 row_mask:0xf bank_mask:0xf
	v_fmac_f32_dpp v232, v60, v156 row_shl:14 row_mask:0xf bank_mask:0xf
	v_fmac_f32_dpp v233, v61, v157 row_shl:14 row_mask:0xf bank_mask:0xf
	v_fmac_f32_dpp v234, v52, v188 row_shl:14 row_mask:0xf bank_mask:0xf
	v_fmac_f32_dpp v235, v53, v189 row_shl:14 row_mask:0xf bank_mask:0xf
	v_mul_f32_e32 v246, v236, v232
	v_mul_f32_e32 v247, v236, v233
	v_exp_f32_e32 v246, v246
	v_exp_f32_e32 v247, v247
	s_nop 0
	v_pk_add_f32 v[246:247], v[246:247], v[238:239]
	v_rcp_f32_e32 v246, v246
	v_rcp_f32_e32 v247, v247
	v_pk_mul_f32 v[232:233], v[232:233], v[234:235]
	v_pk_mul_f32 v[232:233], v[232:233], v[246:247]
	v_cvt_pk_bf16_f32 v48, v232, v233
	v_pk_fma_f32 v[232:233], v[60:61], v[172:173], v[180:181]
	v_pk_fma_f32 v[234:235], v[52:53], v[204:205], v[212:213]
	s_nop 1
	v_fmac_f32_dpp v232, v60, v164 row_shr:1 row_mask:0xf bank_mask:0xf
	v_fmac_f32_dpp v233, v61, v165 row_shr:1 row_mask:0xf bank_mask:0xf
	v_fmac_f32_dpp v234, v52, v196 row_shr:1 row_mask:0xf bank_mask:0xf
	v_fmac_f32_dpp v235, v53, v197 row_shr:1 row_mask:0xf bank_mask:0xf
	v_fmac_f32_dpp v232, v60, v156 row_shr:2 row_mask:0xf bank_mask:0xf
	v_fmac_f32_dpp v233, v61, v157 row_shr:2 row_mask:0xf bank_mask:0xf
	v_fmac_f32_dpp v234, v52, v188 row_shr:2 row_mask:0xf bank_mask:0xf
	v_fmac_f32_dpp v235, v53, v189 row_shr:2 row_mask:0xf bank_mask:0xf
	v_mul_f32_e32 v246, v236, v232
	v_mul_f32_e32 v247, v236, v233
	v_exp_f32_e32 v246, v246
	v_exp_f32_e32 v247, v247
	s_nop 0
	v_pk_add_f32 v[246:247], v[246:247], v[238:239]
	v_rcp_f32_e32 v246, v246
	v_rcp_f32_e32 v247, v247
	v_pk_mul_f32 v[232:233], v[232:233], v[234:235]
	v_pk_mul_f32 v[232:233], v[232:233], v[246:247]
	v_cvt_pk_bf16_f32 v60, v232, v233
	v_pk_fma_f32 v[232:233], v[18:19], v[174:175], v[182:183]
	v_pk_fma_f32 v[234:235], v[6:7], v[206:207], v[214:215]
	s_nop 1
	v_fmac_f32_dpp v232, v18, v166 row_shr:1 row_mask:0xf bank_mask:0xf
	v_fmac_f32_dpp v233, v19, v167 row_shr:1 row_mask:0xf bank_mask:0xf
	v_fmac_f32_dpp v234, v6, v198 row_shr:1 row_mask:0xf bank_mask:0xf
	v_fmac_f32_dpp v235, v7, v199 row_shr:1 row_mask:0xf bank_mask:0xf
	v_fmac_f32_dpp v232, v18, v158 row_shr:2 row_mask:0xf bank_mask:0xf
; __device__ __forceinline__ unsigned cvt_pk_bf16(float lo, float hi) { unsigned r; asm("v_cvt_pk_bf16_f32 %0, %1, %2" : "=v"(r) : "v"(lo), "v"(hi)); return r; }
; __device__ __forceinline__ float sigmoid_f(float v) { return __builtin_amdgcn_rcpf(1.0f + __builtin_amdgcn_exp2f(-1.4426950409f * v)); }
; __device__ __forceinline__ f32x4 bf4(u32x2 w) { return (f32x4){bf_lo(w.x), bf_hi(w.x), bf_lo(w.y), bf_hi(w.y)}; }
; __device__ __forceinline__ void phase10(const Args& a, int G, int wv, bool dummy = false) {
;     ...
;             for (int t = 0; t < 8; ++t) { const f32x4 gc = bf4(gr[t]), vc = bf4(vr[t]);
;                 const f32x4 gg = wg0 * gm2 + wg1 * gm1 + wg2 * gc + bg, vv = wv0 * vm2 + wv1 * vm1 + wv2 * vc + bv;
;                 f32x4 o;
; #pragma unroll
;                 for (int e = 0; e < 4; ++e) o[e] = gg[e] * pg8::sigmoid_f(gg[e]) * vv[e];
;                 u32x2 w; w.x = cvt_pk_bf16(o[0], o[1]); w.y = cvt_pk_bf16(o[2], o[3]);
;                 if (dummy) *(u32x2*)((bf16_t*)(a.ws + WS_D) + ((((size_t)(row0 + t0 + t)) * 5632 + ch) & (size_t)0x1ffffff)) = w; else *(u32x2*)(up + (size_t)(t0 + t) * 5632) = w;
	v_fmac_f32_dpp v233, v19, v159 row_shr:2 row_mask:0xf bank_mask:0xf
	v_fmac_f32_dpp v234, v6, v190 row_shr:2 row_mask:0xf bank_mask:0xf
	v_fmac_f32_dpp v235, v7, v191 row_shr:2 row_mask:0xf bank_mask:0xf
	v_fmac_f32_dpp v232, v34, v166 row_shl:15 row_mask:0xf bank_mask:0xf
	v_fmac_f32_dpp v233, v35, v167 row_shl:15 row_mask:0xf bank_mask:0xf
	v_fmac_f32_dpp v234, v22, v198 row_shl:15 row_mask:0xf bank_mask:0xf
	v_fmac_f32_dpp v235, v23, v199 row_shl:15 row_mask:0xf bank_mask:0xf
	v_fmac_f32_dpp v232, v34, v158 row_shl:14 row_mask:0xf bank_mask:0xf
	v_fmac_f32_dpp v233, v35, v159 row_shl:14 row_mask:0xf bank_mask:0xf
	v_fmac_f32_dpp v234, v22, v190 row_shl:14 row_mask:0xf bank_mask:0xf
	v_fmac_f32_dpp v235, v23, v191 row_shl:14 row_mask:0xf bank_mask:0xf
	v_mul_f32_e32 v246, v236, v232
	v_mul_f32_e32 v247, v236, v233
	v_exp_f32_e32 v246, v246
	v_exp_f32_e32 v247, v247
	s_nop 0
	v_pk_add_f32 v[246:247], v[246:247], v[238:239]
	v_rcp_f32_e32 v246, v246
	v_rcp_f32_e32 v247, v247
	v_pk_mul_f32 v[232:233], v[232:233], v[234:235]
	v_pk_mul_f32 v[232:233], v[232:233], v[246:247]
	v_cvt_pk_bf16_f32 v17, v232, v233
	v_pk_fma_f32 v[232:233], v[34:35], v[174:175], v[182:183]
	v_pk_fma_f32 v[234:235], v[22:23], v[206:207], v[214:215]
	s_nop 1
	v_fmac_f32_dpp v232, v34, v166 row_shr:1 row_mask:0xf bank_mask:0xf
	v_fmac_f32_dpp v233, v35, v167 row_shr:1 row_mask:0xf bank_mask:0xf
	v_fmac_f32_dpp v234, v22, v198 row_shr:1 row_mask:0xf bank_mask:0xf
	v_fmac_f32_dpp v235, v23, v199 row_shr:1 row_mask:0xf bank_mask:0xf
	v_fmac_f32_dpp v232, v34, v158 row_shr:2 row_mask:0xf bank_mask:0xf
	v_fmac_f32_dpp v233, v35, v159 row_shr:2 row_mask:0xf bank_mask:0xf
	v_fmac_f32_dpp v234, v22, v190 row_shr:2 row_mask:0xf bank_mask:0xf
	v_fmac_f32_dpp v235, v23, v191 row_shr:2 row_mask:0xf bank_mask:0xf
	v_fmac_f32_dpp v232, v50, v166 row_shl:15 row_mask:0xf bank_mask:0xf
	v_fmac_f32_dpp v233, v51, v167 row_shl:15 row_mask:0xf bank_mask:0xf
	v_fmac_f32_dpp v234, v38, v198 row_shl:15 row_mask:0xf bank_mask:0xf
	v_fmac_f32_dpp v235, v39, v199 row_shl:15 row_mask:0xf bank_mask:0xf
	v_fmac_f32_dpp v232, v50, v158 row_shl:14 row_mask:0xf bank_mask:0xf
	v_fmac_f32_dpp v233, v51, v159 row_shl:14 row_mask:0xf bank_mask:0xf
	v_fmac_f32_dpp v234, v38, v190 row_shl:14 row_mask:0xf bank_mask:0xf
	v_fmac_f32_dpp v235, v39, v191 row_shl:14 row_mask:0xf bank_mask:0xf
	v_mul_f32_e32 v246, v236, v232
	v_mul_f32_e32 v247, v236, v233
	v_exp_f32_e32 v246, v246
	v_exp_f32_e32 v247, v247
	s_nop 0
	v_pk_add_f32 v[246:247], v[246:247], v[238:239]
	v_rcp_f32_e32 v246, v246
	v_rcp_f32_e32 v247, v247
	v_pk_mul_f32 v[232:233], v[232:233], v[234:235]
	v_pk_mul_f32 v[232:233], v[232:233], v[246:247]
	v_cvt_pk_bf16_f32 v33, v232, v233
	v_pk_fma_f32 v[232:233], v[50:51], v[174:175], v[182:183]
	v_pk_fma_f32 v[234:235], v[38:39], v[206:207], v[214:215]
	s_nop 1
	v_fmac_f32_dpp v232, v50, v166 row_shr:1 row_mask:0xf bank_mask:0xf
	v_fmac_f32_dpp v233, v51, v167 row_shr:1 row_mask:0xf bank_mask:0xf
	v_fmac_f32_dpp v234, v38, v198 row_shr:1 row_mask:0xf bank_mask:0xf
	v_fmac_f32_dpp v235, v39, v199 row_shr:1 row_mask:0xf bank_mask:0xf
	v_fmac_f32_dpp v232, v50, v158 row_shr:2 row_mask:0xf bank_mask:0xf
	v_fmac_f32_dpp v233, v51, v159 row_shr:2 row_mask:0xf bank_mask:0xf
	v_fmac_f32_dpp v234, v38, v190 row_shr:2 row_mask:0xf bank_mask:0xf
	v_fmac_f32_dpp v235, v39, v191 row_shr:2 row_mask:0xf bank_mask:0xf
	v_fmac_f32_dpp v232, v62, v166 row_shl:15 row_mask:0xf bank_mask:0xf
	v_fmac_f32_dpp v233, v63, v167 row_shl:15 row_mask:0xf bank_mask:0xf
	v_fmac_f32_dpp v234, v54, v198 row_shl:15 row_mask:0xf bank_mask:0xf
	v_fmac_f32_dpp v235, v55, v199 row_shl:15 row_mask:0xf bank_mask:0xf
	v_fmac_f32_dpp v232, v62, v158 row_shl:14 row_mask:0xf bank_mask:0xf
	v_fmac_f32_dpp v233, v63, v159 row_shl:14 row_mask:0xf bank_mask:0xf
	v_fmac_f32_dpp v234, v54, v190 row_shl:14 row_mask:0xf bank_mask:0xf
	v_fmac_f32_dpp v235, v55, v191 row_shl:14 row_mask:0xf bank_mask:0xf
	v_mul_f32_e32 v246, v236, v232
	v_mul_f32_e32 v247, v236, v233
	v_exp_f32_e32 v246, v246
	v_exp_f32_e32 v247, v247
	s_nop 0
	v_pk_add_f32 v[246:247], v[246:247], v[238:239]
	v_rcp_f32_e32 v246, v246
	v_rcp_f32_e32 v247, v247
	v_pk_mul_f32 v[232:233], v[232:233], v[234:235]
	v_pk_mul_f32 v[232:233], v[232:233], v[246:247]
	v_cvt_pk_bf16_f32 v49, v232, v233
	v_pk_fma_f32 v[232:233], v[62:63], v[174:175], v[182:183]
	v_pk_fma_f32 v[234:235], v[54:55], v[206:207], v[214:215]
	s_nop 1
	v_fmac_f32_dpp v232, v62, v166 row_shr:1 row_mask:0xf bank_mask:0xf
	v_fmac_f32_dpp v233, v63, v167 row_shr:1 row_mask:0xf bank_mask:0xf
	v_fmac_f32_dpp v234, v54, v198 row_shr:1 row_mask:0xf bank_mask:0xf
	v_fmac_f32_dpp v235, v55, v199 row_shr:1 row_mask:0xf bank_mask:0xf
	v_fmac_f32_dpp v232, v62, v158 row_shr:2 row_mask:0xf bank_mask:0xf
	v_fmac_f32_dpp v233, v63, v159 row_shr:2 row_mask:0xf bank_mask:0xf
	v_fmac_f32_dpp v234, v54, v190 row_shr:2 row_mask:0xf bank_mask:0xf
	v_fmac_f32_dpp v235, v55, v191 row_shr:2 row_mask:0xf bank_mask:0xf
	v_mul_f32_e32 v246, v236, v232
	v_mul_f32_e32 v247, v236, v233
	v_exp_f32_e32 v246, v246
	v_exp_f32_e32 v247, v247
	s_nop 0
	v_pk_add_f32 v[246:247], v[246:247], v[238:239]
	v_rcp_f32_e32 v246, v246
	v_rcp_f32_e32 v247, v247
	v_pk_mul_f32 v[232:233], v[232:233], v[234:235]
	v_pk_mul_f32 v[232:233], v[232:233], v[246:247]
	v_cvt_pk_bf16_f32 v61, v232, v233
	v_pk_fma_f32 v[232:233], v[8:9], v[176:177], v[184:185]
	v_pk_fma_f32 v[234:235], v[0:1], v[208:209], v[216:217]
	s_nop 1
	v_fmac_f32_dpp v232, v8, v168 row_shr:1 row_mask:0xf bank_mask:0xf
	v_fmac_f32_dpp v233, v9, v169 row_shr:1 row_mask:0xf bank_mask:0xf
; __device__ __forceinline__ unsigned cvt_pk_bf16(float lo, float hi) { unsigned r; asm("v_cvt_pk_bf16_f32 %0, %1, %2" : "=v"(r) : "v"(lo), "v"(hi)); return r; }
; __device__ __forceinline__ float sigmoid_f(float v) { return __builtin_amdgcn_rcpf(1.0f + __builtin_amdgcn_exp2f(-1.4426950409f * v)); }
; __device__ __forceinline__ f32x4 bf4(u32x2 w) { return (f32x4){bf_lo(w.x), bf_hi(w.x), bf_lo(w.y), bf_hi(w.y)}; }
; __device__ __forceinline__ void phase10(const Args& a, int G, int wv, bool dummy = false) {
;     ...
;             for (int t = 0; t < 8; ++t) { const f32x4 gc = bf4(gr[t]), vc = bf4(vr[t]);
;                 const f32x4 gg = wg0 * gm2 + wg1 * gm1 + wg2 * gc + bg, vv = wv0 * vm2 + wv1 * vm1 + wv2 * vc + bv;
;                 f32x4 o;
; #pragma unroll
;                 for (int e = 0; e < 4; ++e) o[e] = gg[e] * pg8::sigmoid_f(gg[e]) * vv[e];
;                 u32x2 w; w.x = cvt_pk_bf16(o[0], o[1]); w.y = cvt_pk_bf16(o[2], o[3]);
;                 if (dummy) *(u32x2*)((bf16_t*)(a.ws + WS_D) + ((((size_t)(row0 + t0 + t)) * 5632 + ch) & (size_t)0x1ffffff)) = w; else *(u32x2*)(up + (size_t)(t0 + t) * 5632) = w;
	v_fmac_f32_dpp v234, v0, v200 row_shr:1 row_mask:0xf bank_mask:0xf
	v_fmac_f32_dpp v235, v1, v201 row_shr:1 row_mask:0xf bank_mask:0xf
	v_fmac_f32_dpp v232, v8, v160 row_shr:2 row_mask:0xf bank_mask:0xf
	v_fmac_f32_dpp v233, v9, v161 row_shr:2 row_mask:0xf bank_mask:0xf
	v_fmac_f32_dpp v234, v0, v192 row_shr:2 row_mask:0xf bank_mask:0xf
	v_fmac_f32_dpp v235, v1, v193 row_shr:2 row_mask:0xf bank_mask:0xf
	v_fmac_f32_dpp v232, v24, v168 row_shl:15 row_mask:0xf bank_mask:0xf
	v_fmac_f32_dpp v233, v25, v169 row_shl:15 row_mask:0xf bank_mask:0xf
	v_fmac_f32_dpp v234, v12, v200 row_shl:15 row_mask:0xf bank_mask:0xf
	v_fmac_f32_dpp v235, v13, v201 row_shl:15 row_mask:0xf bank_mask:0xf
	v_fmac_f32_dpp v232, v24, v160 row_shl:14 row_mask:0xf bank_mask:0xf
	v_fmac_f32_dpp v233, v25, v161 row_shl:14 row_mask:0xf bank_mask:0xf
	v_fmac_f32_dpp v234, v12, v192 row_shl:14 row_mask:0xf bank_mask:0xf
	v_fmac_f32_dpp v235, v13, v193 row_shl:14 row_mask:0xf bank_mask:0xf
	v_mul_f32_e32 v246, v236, v232
	v_mul_f32_e32 v247, v236, v233
	v_exp_f32_e32 v246, v246
	v_exp_f32_e32 v247, v247
	s_nop 0
	v_pk_add_f32 v[246:247], v[246:247], v[238:239]
	v_rcp_f32_e32 v246, v246
	v_rcp_f32_e32 v247, v247
	v_pk_mul_f32 v[232:233], v[232:233], v[234:235]
	v_pk_mul_f32 v[232:233], v[232:233], v[246:247]
	v_cvt_pk_bf16_f32 v18, v232, v233
	v_pk_fma_f32 v[232:233], v[24:25], v[176:177], v[184:185]
	v_pk_fma_f32 v[234:235], v[12:13], v[208:209], v[216:217]
	s_nop 1
	v_fmac_f32_dpp v232, v24, v168 row_shr:1 row_mask:0xf bank_mask:0xf
	v_fmac_f32_dpp v233, v25, v169 row_shr:1 row_mask:0xf bank_mask:0xf
	v_fmac_f32_dpp v234, v12, v200 row_shr:1 row_mask:0xf bank_mask:0xf
	v_fmac_f32_dpp v235, v13, v201 row_shr:1 row_mask:0xf bank_mask:0xf
	v_fmac_f32_dpp v232, v24, v160 row_shr:2 row_mask:0xf bank_mask:0xf
	v_fmac_f32_dpp v233, v25, v161 row_shr:2 row_mask:0xf bank_mask:0xf
	v_fmac_f32_dpp v234, v12, v192 row_shr:2 row_mask:0xf bank_mask:0xf
	v_fmac_f32_dpp v235, v13, v193 row_shr:2 row_mask:0xf bank_mask:0xf
	v_fmac_f32_dpp v232, v40, v168 row_shl:15 row_mask:0xf bank_mask:0xf
	v_fmac_f32_dpp v233, v41, v169 row_shl:15 row_mask:0xf bank_mask:0xf
	v_fmac_f32_dpp v234, v28, v200 row_shl:15 row_mask:0xf bank_mask:0xf
	v_fmac_f32_dpp v235, v29, v201 row_shl:15 row_mask:0xf bank_mask:0xf
	v_fmac_f32_dpp v232, v40, v160 row_shl:14 row_mask:0xf bank_mask:0xf
	v_fmac_f32_dpp v233, v41, v161 row_shl:14 row_mask:0xf bank_mask:0xf
	v_fmac_f32_dpp v234, v28, v192 row_shl:14 row_mask:0xf bank_mask:0xf
	v_fmac_f32_dpp v235, v29, v193 row_shl:14 row_mask:0xf bank_mask:0xf
	v_mul_f32_e32 v246, v236, v232
	v_mul_f32_e32 v247, v236, v233
	v_exp_f32_e32 v246, v246
	v_exp_f32_e32 v247, v247
	s_nop 0
	v_pk_add_f32 v[246:247], v[246:247], v[238:239]
	v_rcp_f32_e32 v246, v246
	v_rcp_f32_e32 v247, v247
	v_pk_mul_f32 v[232:233], v[232:233], v[234:235]
	v_pk_mul_f32 v[232:233], v[232:233], v[246:247]
	v_cvt_pk_bf16_f32 v34, v232, v233
	v_pk_fma_f32 v[232:233], v[40:41], v[176:177], v[184:185]
	v_pk_fma_f32 v[234:235], v[28:29], v[208:209], v[216:217]
	s_nop 1
	v_fmac_f32_dpp v232, v40, v168 row_shr:1 row_mask:0xf bank_mask:0xf
	v_fmac_f32_dpp v233, v41, v169 row_shr:1 row_mask:0xf bank_mask:0xf
	v_fmac_f32_dpp v234, v28, v200 row_shr:1 row_mask:0xf bank_mask:0xf
	v_fmac_f32_dpp v235, v29, v201 row_shr:1 row_mask:0xf bank_mask:0xf
	v_fmac_f32_dpp v232, v40, v160 row_shr:2 row_mask:0xf bank_mask:0xf
	v_fmac_f32_dpp v233, v41, v161 row_shr:2 row_mask:0xf bank_mask:0xf
	v_fmac_f32_dpp v234, v28, v192 row_shr:2 row_mask:0xf bank_mask:0xf
	v_fmac_f32_dpp v235, v29, v193 row_shr:2 row_mask:0xf bank_mask:0xf
	v_fmac_f32_dpp v232, v56, v168 row_shl:15 row_mask:0xf bank_mask:0xf
	v_fmac_f32_dpp v233, v57, v169 row_shl:15 row_mask:0xf bank_mask:0xf
	v_fmac_f32_dpp v234, v44, v200 row_shl:15 row_mask:0xf bank_mask:0xf
	v_fmac_f32_dpp v235, v45, v201 row_shl:15 row_mask:0xf bank_mask:0xf
	v_fmac_f32_dpp v232, v56, v160 row_shl:14 row_mask:0xf bank_mask:0xf
	v_fmac_f32_dpp v233, v57, v161 row_shl:14 row_mask:0xf bank_mask:0xf
	v_fmac_f32_dpp v234, v44, v192 row_shl:14 row_mask:0xf bank_mask:0xf
	v_fmac_f32_dpp v235, v45, v193 row_shl:14 row_mask:0xf bank_mask:0xf
	v_mul_f32_e32 v246, v236, v232
	v_mul_f32_e32 v247, v236, v233
	v_exp_f32_e32 v246, v246
	v_exp_f32_e32 v247, v247
	s_nop 0
	v_pk_add_f32 v[246:247], v[246:247], v[238:239]
	v_rcp_f32_e32 v246, v246
	v_rcp_f32_e32 v247, v247
	v_pk_mul_f32 v[232:233], v[232:233], v[234:235]
	v_pk_mul_f32 v[232:233], v[232:233], v[246:247]
	v_cvt_pk_bf16_f32 v50, v232, v233
	v_pk_fma_f32 v[232:233], v[56:57], v[176:177], v[184:185]
	v_pk_fma_f32 v[234:235], v[44:45], v[208:209], v[216:217]
	s_nop 1
	v_fmac_f32_dpp v232, v56, v168 row_shr:1 row_mask:0xf bank_mask:0xf
	v_fmac_f32_dpp v233, v57, v169 row_shr:1 row_mask:0xf bank_mask:0xf
	v_fmac_f32_dpp v234, v44, v200 row_shr:1 row_mask:0xf bank_mask:0xf
	v_fmac_f32_dpp v235, v45, v201 row_shr:1 row_mask:0xf bank_mask:0xf
	v_fmac_f32_dpp v232, v56, v160 row_shr:2 row_mask:0xf bank_mask:0xf
	v_fmac_f32_dpp v233, v57, v161 row_shr:2 row_mask:0xf bank_mask:0xf
	v_fmac_f32_dpp v234, v44, v192 row_shr:2 row_mask:0xf bank_mask:0xf
	v_fmac_f32_dpp v235, v45, v193 row_shr:2 row_mask:0xf bank_mask:0xf
	v_mul_f32_e32 v246, v236, v232
	v_mul_f32_e32 v247, v236, v233
	v_exp_f32_e32 v246, v246
	v_exp_f32_e32 v247, v247
	s_nop 0
	v_pk_add_f32 v[246:247], v[246:247], v[238:239]
	v_rcp_f32_e32 v246, v246
	v_rcp_f32_e32 v247, v247
	v_pk_mul_f32 v[232:233], v[232:233], v[234:235]
	v_pk_mul_f32 v[232:233], v[232:233], v[246:247]
	v_cvt_pk_bf16_f32 v62, v232, v233
	v_pk_fma_f32 v[232:233], v[10:11], v[178:179], v[186:187]
; __device__ __forceinline__ unsigned cvt_pk_bf16(float lo, float hi) { unsigned r; asm("v_cvt_pk_bf16_f32 %0, %1, %2" : "=v"(r) : "v"(lo), "v"(hi)); return r; }
; __device__ __forceinline__ float sigmoid_f(float v) { return __builtin_amdgcn_rcpf(1.0f + __builtin_amdgcn_exp2f(-1.4426950409f * v)); }
; __device__ __forceinline__ u32x4 pack8(f32x4 a, f32x4 b) { u32x4 w; w.x = cvt_pk_bf16(a[0], a[1]); w.y = cvt_pk_bf16(a[2], a[3]); w.z = cvt_pk_bf16(b[0], b[1]); w.w = cvt_pk_bf16(b[2], b[3]); return w; }
; __device__ __forceinline__ f32x4 bf4(u32x2 w) { return (f32x4){bf_lo(w.x), bf_hi(w.x), bf_lo(w.y), bf_hi(w.y)}; }
;     __device__ __forceinline__ void operator()(const f32x4 (&acc)[2][2][4][2], const Unit& u, int wr, int wc, int fr, int fq) const {
;     ...
;             for (int m = 0; m < 4; ++m) { const int row = row0 + ai * HALF + m * 16; bf16_t* rowp = UP + (size_t)row * 5632 + u.pn * HALF + wc * 32 + 8 * fq;
; #pragma unroll
;                 for (int bj = 0; bj < 2; ++bj) { const u32x4 w = pack8(acc[ai][bj][m][0], acc[ai][bj][m][1]); __builtin_nontemporal_store(w, (u32x4*)(rowp + (size_t)bj * ((size_t)16384 * 5632)));
; __device__ __forceinline__ void phase10(const Args& a, int G, int wv, bool dummy = false) {
;     ...
;             for (int t = 0; t < 8; ++t) { const f32x4 gc = bf4(gr[t]), vc = bf4(vr[t]);
;                 const f32x4 gg = wg0 * gm2 + wg1 * gm1 + wg2 * gc + bg, vv = wv0 * vm2 + wv1 * vm1 + wv2 * vc + bv;
;                 f32x4 o;
; #pragma unroll
;                 for (int e = 0; e < 4; ++e) o[e] = gg[e] * pg8::sigmoid_f(gg[e]) * vv[e];
;                 u32x2 w; w.x = cvt_pk_bf16(o[0], o[1]); w.y = cvt_pk_bf16(o[2], o[3]);
;                 if (dummy) *(u32x2*)((bf16_t*)(a.ws + WS_D) + ((((size_t)(row0 + t0 + t)) * 5632 + ch) & (size_t)0x1ffffff)) = w; else *(u32x2*)(up + (size_t)(t0 + t) * 5632) = w;
	v_pk_fma_f32 v[234:235], v[2:3], v[210:211], v[218:219]
	s_nop 1
	v_fmac_f32_dpp v232, v10, v170 row_shr:1 row_mask:0xf bank_mask:0xf
	v_fmac_f32_dpp v233, v11, v171 row_shr:1 row_mask:0xf bank_mask:0xf
	v_fmac_f32_dpp v234, v2, v202 row_shr:1 row_mask:0xf bank_mask:0xf
	v_fmac_f32_dpp v235, v3, v203 row_shr:1 row_mask:0xf bank_mask:0xf
	v_fmac_f32_dpp v232, v10, v162 row_shr:2 row_mask:0xf bank_mask:0xf
	v_fmac_f32_dpp v233, v11, v163 row_shr:2 row_mask:0xf bank_mask:0xf
	v_fmac_f32_dpp v234, v2, v194 row_shr:2 row_mask:0xf bank_mask:0xf
	v_fmac_f32_dpp v235, v3, v195 row_shr:2 row_mask:0xf bank_mask:0xf
	v_fmac_f32_dpp v232, v26, v170 row_shl:15 row_mask:0xf bank_mask:0xf
	v_fmac_f32_dpp v233, v27, v171 row_shl:15 row_mask:0xf bank_mask:0xf
	v_fmac_f32_dpp v234, v14, v202 row_shl:15 row_mask:0xf bank_mask:0xf
	v_fmac_f32_dpp v235, v15, v203 row_shl:15 row_mask:0xf bank_mask:0xf
	v_fmac_f32_dpp v232, v26, v162 row_shl:14 row_mask:0xf bank_mask:0xf
	v_fmac_f32_dpp v233, v27, v163 row_shl:14 row_mask:0xf bank_mask:0xf
	v_fmac_f32_dpp v234, v14, v194 row_shl:14 row_mask:0xf bank_mask:0xf
	v_fmac_f32_dpp v235, v15, v195 row_shl:14 row_mask:0xf bank_mask:0xf
	v_mul_f32_e32 v246, v236, v232
	v_mul_f32_e32 v247, v236, v233
	v_exp_f32_e32 v246, v246
	v_exp_f32_e32 v247, v247
	s_nop 0
	v_pk_add_f32 v[246:247], v[246:247], v[238:239]
	v_rcp_f32_e32 v246, v246
	v_rcp_f32_e32 v247, v247
	v_pk_mul_f32 v[232:233], v[232:233], v[234:235]
	v_pk_mul_f32 v[232:233], v[232:233], v[246:247]
	v_cvt_pk_bf16_f32 v19, v232, v233
	v_pk_fma_f32 v[232:233], v[26:27], v[178:179], v[186:187]
	v_pk_fma_f32 v[234:235], v[14:15], v[210:211], v[218:219]
	s_nop 1
	v_fmac_f32_dpp v232, v26, v170 row_shr:1 row_mask:0xf bank_mask:0xf
	v_fmac_f32_dpp v233, v27, v171 row_shr:1 row_mask:0xf bank_mask:0xf
	v_fmac_f32_dpp v234, v14, v202 row_shr:1 row_mask:0xf bank_mask:0xf
	v_fmac_f32_dpp v235, v15, v203 row_shr:1 row_mask:0xf bank_mask:0xf
	v_fmac_f32_dpp v232, v26, v162 row_shr:2 row_mask:0xf bank_mask:0xf
	v_fmac_f32_dpp v233, v27, v163 row_shr:2 row_mask:0xf bank_mask:0xf
	v_fmac_f32_dpp v234, v14, v194 row_shr:2 row_mask:0xf bank_mask:0xf
	v_fmac_f32_dpp v235, v15, v195 row_shr:2 row_mask:0xf bank_mask:0xf
	v_fmac_f32_dpp v232, v42, v170 row_shl:15 row_mask:0xf bank_mask:0xf
	v_fmac_f32_dpp v233, v43, v171 row_shl:15 row_mask:0xf bank_mask:0xf
	v_fmac_f32_dpp v234, v30, v202 row_shl:15 row_mask:0xf bank_mask:0xf
	v_fmac_f32_dpp v235, v31, v203 row_shl:15 row_mask:0xf bank_mask:0xf
	v_fmac_f32_dpp v232, v42, v162 row_shl:14 row_mask:0xf bank_mask:0xf
	v_fmac_f32_dpp v233, v43, v163 row_shl:14 row_mask:0xf bank_mask:0xf
	v_fmac_f32_dpp v234, v30, v194 row_shl:14 row_mask:0xf bank_mask:0xf
	v_fmac_f32_dpp v235, v31, v195 row_shl:14 row_mask:0xf bank_mask:0xf
	v_mul_f32_e32 v246, v236, v232
	v_mul_f32_e32 v247, v236, v233
	v_exp_f32_e32 v246, v246
	v_exp_f32_e32 v247, v247
	s_nop 0
	v_pk_add_f32 v[246:247], v[246:247], v[238:239]
	v_rcp_f32_e32 v246, v246
	v_rcp_f32_e32 v247, v247
	v_pk_mul_f32 v[232:233], v[232:233], v[234:235]
	v_pk_mul_f32 v[232:233], v[232:233], v[246:247]
	v_cvt_pk_bf16_f32 v35, v232, v233
	v_pk_fma_f32 v[232:233], v[42:43], v[178:179], v[186:187]
	v_pk_fma_f32 v[234:235], v[30:31], v[210:211], v[218:219]
	s_nop 1
	v_fmac_f32_dpp v232, v42, v170 row_shr:1 row_mask:0xf bank_mask:0xf
	v_fmac_f32_dpp v233, v43, v171 row_shr:1 row_mask:0xf bank_mask:0xf
	v_fmac_f32_dpp v234, v30, v202 row_shr:1 row_mask:0xf bank_mask:0xf
	v_fmac_f32_dpp v235, v31, v203 row_shr:1 row_mask:0xf bank_mask:0xf
	v_fmac_f32_dpp v232, v42, v162 row_shr:2 row_mask:0xf bank_mask:0xf
	v_fmac_f32_dpp v233, v43, v163 row_shr:2 row_mask:0xf bank_mask:0xf
	v_fmac_f32_dpp v234, v30, v194 row_shr:2 row_mask:0xf bank_mask:0xf
	v_fmac_f32_dpp v235, v31, v195 row_shr:2 row_mask:0xf bank_mask:0xf
	v_fmac_f32_dpp v232, v58, v170 row_shl:15 row_mask:0xf bank_mask:0xf
	v_fmac_f32_dpp v233, v59, v171 row_shl:15 row_mask:0xf bank_mask:0xf
	v_fmac_f32_dpp v234, v46, v202 row_shl:15 row_mask:0xf bank_mask:0xf
	v_fmac_f32_dpp v235, v47, v203 row_shl:15 row_mask:0xf bank_mask:0xf
	v_fmac_f32_dpp v232, v58, v162 row_shl:14 row_mask:0xf bank_mask:0xf
	v_fmac_f32_dpp v233, v59, v163 row_shl:14 row_mask:0xf bank_mask:0xf
	v_fmac_f32_dpp v234, v46, v194 row_shl:14 row_mask:0xf bank_mask:0xf
	v_fmac_f32_dpp v235, v47, v195 row_shl:14 row_mask:0xf bank_mask:0xf
	v_mul_f32_e32 v246, v236, v232
	v_mul_f32_e32 v247, v236, v233
	v_exp_f32_e32 v246, v246
	v_exp_f32_e32 v247, v247
	s_nop 0
	v_pk_add_f32 v[246:247], v[246:247], v[238:239]
	v_rcp_f32_e32 v246, v246
	v_rcp_f32_e32 v247, v247
	v_pk_mul_f32 v[232:233], v[232:233], v[234:235]
	v_pk_mul_f32 v[232:233], v[232:233], v[246:247]
	v_cvt_pk_bf16_f32 v51, v232, v233
	v_pk_fma_f32 v[232:233], v[58:59], v[178:179], v[186:187]
	v_pk_fma_f32 v[234:235], v[46:47], v[210:211], v[218:219]
	s_nop 1
	v_fmac_f32_dpp v232, v58, v170 row_shr:1 row_mask:0xf bank_mask:0xf
	v_fmac_f32_dpp v233, v59, v171 row_shr:1 row_mask:0xf bank_mask:0xf
	v_fmac_f32_dpp v234, v46, v202 row_shr:1 row_mask:0xf bank_mask:0xf
	v_fmac_f32_dpp v235, v47, v203 row_shr:1 row_mask:0xf bank_mask:0xf
	v_fmac_f32_dpp v232, v58, v162 row_shr:2 row_mask:0xf bank_mask:0xf
	v_fmac_f32_dpp v233, v59, v163 row_shr:2 row_mask:0xf bank_mask:0xf
	v_fmac_f32_dpp v234, v46, v194 row_shr:2 row_mask:0xf bank_mask:0xf
	v_fmac_f32_dpp v235, v47, v195 row_shr:2 row_mask:0xf bank_mask:0xf
	v_mul_f32_e32 v246, v236, v232
	v_mul_f32_e32 v247, v236, v233
	v_exp_f32_e32 v246, v246
	v_exp_f32_e32 v247, v247
	s_nop 0
	v_pk_add_f32 v[246:247], v[246:247], v[238:239]
	v_rcp_f32_e32 v246, v246
	v_rcp_f32_e32 v247, v247
	v_pk_mul_f32 v[232:233], v[232:233], v[234:235]
	v_pk_mul_f32 v[232:233], v[232:233], v[246:247]
	v_cvt_pk_bf16_f32 v63, v232, v233
	s_add_u32 s36, s100, 0x160000
	s_addc_u32 s37, s101, 0
	s_andn2_b64 exec, exec, s[64:65]
	global_store_dwordx4 v149, v[60:63], s[36:37] sc1
	s_mov_b64 exec, -1
	s_add_u32 s36, s100, 0x18c000
	s_addc_u32 s37, s101, 0
	global_store_dwordx4 v149, v[48:51], s[36:37] sc1
	s_add_u32 s36, s100, 0x1b8000
	s_addc_u32 s37, s101, 0
	global_store_dwordx4 v149, v[32:35], s[36:37] sc1
	s_add_u32 s36, s100, 0x1e4000
	s_addc_u32 s37, s101, 0
	global_store_dwordx4 v149, v[16:19], s[36:37] sc1
	s_andn2_b64 vcc, exec, s[4:5]
	s_mov_b64 s[4:5], -1
	s_cbranch_vccnz .LBB0_961
	s_andn2_b64 vcc, exec, s[10:11]
	s_cbranch_vccnz .LBB0_960
	s_barrier
	s_branch .LBB0_960
